# non-temporal (nt) policy on the once-read f32 input rows in the layer-0 RMS/convert items
# speedup vs baseline: 1.0727x; 1.0053x over previous
; DEVI int get_tid() { int t = threadIdx.x & 255; asm volatile("" : "+v"(t)); return t; }
; DEVI void rms_rows(const float* __restrict__ x, float* __restrict__ ssq, bfu* __restrict__ dst, int item) {
;   const int lane = get_tid() & 63, wid = get_tid() >> 6;
;   float4 v[4][4];
; #pragma unroll
;   for (int r = 0; r < 4; ++r) {
;     const float4* xr = (const float4*)(x + ((long)item * 16 + wid * 4 + r) * 1024);
; #pragma unroll
;     for (int i = 0; i < 4; ++i) v[r][i] = xr[lane + 64 * i];
;   }
; #pragma unroll
;   for (int r = 0; r < 4; ++r) {
;     long row = (long)item * 16 + wid * 4 + r;
;     float ss = 0.f;
; #pragma unroll
;     for (int i = 0; i < 4; ++i) ss += v[r][i].x * v[r][i].x + v[r][i].y * v[r][i].y + v[r][i].z * v[r][i].z + v[r][i].w * v[r][i].w;
;     ss = wave_sum(ss);
;     if (lane == 0) *(float4*)(ssq + row * 4) = make_float4(ss, 0.f, 0.f, 0.f);
.LBB0_782:
	s_cmpk_gt_i32 s23, 0x1183
	s_mov_b64 s[0:1], -1
	s_cbranch_scc0 .LBB0_803
	s_cmpk_gt_u32 s23, 0x1185
	s_cbranch_scc0 .LBB0_793
	v_mov_b32_e32 v0, v221
	s_lshl_b32 s0, s23, 4
	v_and_b32_e32 v78, 63, v0
	v_mov_b32_e32 v0, v221
	s_add_i32 s30, s0, 0xfffee7a0
	v_ashrrev_i32_e32 v0, 4, v0
	v_and_b32_e32 v2, -4, v0
	v_ashrrev_i32_e32 v3, 31, v2
	v_lshl_add_u64 v[72:73], v[2:3], 0, s[30:31]
	v_lshlrev_b64 v[2:3], 12, v[72:73]
	v_lshl_add_u64 v[2:3], s[4:5], 0, v[2:3]
	v_lshlrev_b32_e32 v0, 4, v78
	v_lshl_add_u64 v[2:3], v[2:3], 0, v[0:1]
	global_load_dwordx4 v[48:51], v[2:3], off nt
	global_load_dwordx4 v[40:43], v[2:3], off offset:1024 nt
	global_load_dwordx4 v[44:47], v[2:3], off offset:2048 nt
	global_load_dwordx4 v[36:39], v[2:3], off offset:3072 nt
	v_or_b32_e32 v74, 1, v72
	v_mov_b32_e32 v75, v73
	v_or_b32_e32 v70, 2, v72
	v_mov_b32_e32 v71, v73
	v_or_b32_e32 v68, 3, v72
	v_mov_b32_e32 v69, v73
	v_lshlrev_b64 v[2:3], 12, v[74:75]
	v_lshlrev_b64 v[4:5], 12, v[70:71]
	v_lshlrev_b64 v[6:7], 12, v[68:69]
	v_lshl_add_u64 v[2:3], s[4:5], 0, v[2:3]
	v_lshl_add_u64 v[4:5], s[4:5], 0, v[4:5]
	v_lshl_add_u64 v[6:7], s[4:5], 0, v[6:7]
	v_lshl_add_u64 v[2:3], v[2:3], 0, v[0:1]
	v_lshl_add_u64 v[4:5], v[4:5], 0, v[0:1]
	v_lshl_add_u64 v[6:7], v[6:7], 0, v[0:1]
	global_load_dwordx4 v[64:67], v[2:3], off nt
	global_load_dwordx4 v[60:63], v[2:3], off offset:1024 nt
	global_load_dwordx4 v[56:59], v[2:3], off offset:2048 nt
	global_load_dwordx4 v[52:55], v[2:3], off offset:3072 nt
	global_load_dwordx4 v[32:35], v[4:5], off nt
	global_load_dwordx4 v[28:31], v[4:5], off offset:1024 nt
	global_load_dwordx4 v[24:27], v[4:5], off offset:2048 nt
	global_load_dwordx4 v[20:23], v[4:5], off offset:3072 nt
	global_load_dwordx4 v[16:19], v[6:7], off nt
	global_load_dwordx4 v[12:15], v[6:7], off offset:1024 nt
	global_load_dwordx4 v[8:11], v[6:7], off offset:2048 nt
	s_nop 0
	global_load_dwordx4 v[4:7], v[6:7], off offset:3072 nt
	v_and_b32_e32 v0, 64, v225
	v_xor_b32_e32 v2, 32, v225
	v_add_u32_e32 v0, 64, v0
	v_cmp_lt_i32_e32 vcc, v2, v0
	s_waitcnt vmcnt(0)
	v_pk_mul_f32 v[76:77], v[50:51], v[50:51]
	v_cndmask_b32_e32 v2, v225, v2, vcc
	v_lshlrev_b32_e32 v79, 2, v2
	v_pk_mul_f32 v[2:3], v[48:49], v[48:49]
	v_pk_mul_f32 v[80:81], v[40:41], v[40:41]
	v_pk_mul_f32 v[82:83], v[42:43], v[42:43]
	v_pk_mul_f32 v[84:85], v[44:45], v[44:45]
	v_add_f32_e32 v80, v80, v81
	v_add_f32_e32 v2, v2, v3
	v_pk_mul_f32 v[86:87], v[46:47], v[46:47]
	v_pk_mul_f32 v[88:89], v[36:37], v[36:37]
	v_add_f32_e32 v3, v84, v85
	v_add_f32_e32 v80, v80, v82
	v_add_f32_e32 v2, v2, v76
	v_pk_mul_f32 v[90:91], v[38:39], v[38:39]
	v_add_f32_e32 v81, v88, v89
	v_add_f32_e32 v3, v3, v86
	v_add_f32_e32 v80, v80, v83
	v_add_f32_e32 v2, v2, v77
	v_add_f32_e32 v76, v81, v90
	v_add_f32_e32 v3, v3, v87
	v_add_f32_e32 v2, v2, v80
	v_add_f32_e32 v76, v76, v91
	v_add_f32_e32 v2, v2, v3
	v_add_f32_e32 v2, v2, v76
	ds_bpermute_b32 v3, v79, v2
	v_xor_b32_e32 v76, 16, v225
	v_cmp_lt_i32_e32 vcc, v76, v0
	s_waitcnt lgkmcnt(0)
	v_add_f32_e32 v2, v2, v3
	v_cndmask_b32_e32 v76, v225, v76, vcc
	v_lshlrev_b32_e32 v80, 2, v76
	ds_bpermute_b32 v3, v80, v2
	v_xor_b32_e32 v76, 8, v225
	v_cmp_lt_i32_e32 vcc, v76, v0
	s_waitcnt lgkmcnt(0)
	v_add_f32_e32 v2, v2, v3
	v_cndmask_b32_e32 v76, v225, v76, vcc
	v_lshlrev_b32_e32 v81, 2, v76
	ds_bpermute_b32 v3, v81, v2
	v_xor_b32_e32 v76, 4, v225
	v_cmp_lt_i32_e32 vcc, v76, v0
	s_waitcnt lgkmcnt(0)
	v_add_f32_e32 v2, v2, v3
	v_cndmask_b32_e32 v76, v225, v76, vcc
	v_lshlrev_b32_e32 v82, 2, v76
	ds_bpermute_b32 v3, v82, v2
	v_xor_b32_e32 v76, 2, v225
	v_cmp_lt_i32_e32 vcc, v76, v0
	s_waitcnt lgkmcnt(0)
	v_add_f32_e32 v2, v2, v3
	v_cndmask_b32_e32 v76, v225, v76, vcc
	v_lshlrev_b32_e32 v83, 2, v76
	ds_bpermute_b32 v3, v83, v2
	v_xor_b32_e32 v76, 1, v225
	v_cmp_lt_i32_e32 vcc, v76, v0
	s_nop 1
	v_cndmask_b32_e32 v0, v225, v76, vcc
	v_lshlrev_b32_e32 v84, 2, v0
	s_waitcnt lgkmcnt(0)
	v_add_f32_e32 v0, v2, v3
	ds_bpermute_b32 v2, v84, v0
	v_cmp_eq_u32_e32 vcc, 0, v78
	s_and_saveexec_b64 s[0:1], vcc
	s_cbranch_execz .LBB0_786
	v_readlane_b32 s36, v244, 55
	v_readlane_b32 s37, v244, 56
	s_waitcnt lgkmcnt(0)
	v_add_f32_e32 v0, v0, v2
	v_mov_b32_e32 v2, v1
	v_lshl_add_u64 v[76:77], v[72:73], 4, s[36:37]
	v_mov_b32_e32 v3, v1
	global_store_dwordx4 v[76:77], v[0:3], off
